# window attention: next unit's Q fragments loaded ahead of the current unit's output stores; K/V-loop wait leaves the stores in flight
# speedup vs baseline: 1.0053x; 1.0053x over previous
.LBB0_922:
	v_mov_b32_e32 v0, v235
	s_nop 1
	v_permlane32_swap_b32_e32 v235, v0
	v_add_f32_e32 v0, v235, v0
	v_div_scale_f32 v2, s[2:3], v0, v0, 1.0
	v_rcp_f32_e32 v3, v2
	s_add_i32 s4, s4, 1
	s_cmp_eq_u32 s4, 4
	s_cbranch_scc1 .Lwq_nopf
	s_max_u32 s0, s4, 2
	s_and_b64 s[2:3], s[18:19], exec
	s_cselect_b32 s9, s0, s4
	s_or_b32 s0, s4, 4
	s_min_u32 s10, s0, s15
	s_cmp_gt_u32 s9, s10
	s_cbranch_scc1 .Lwq_nopf
	s_lshl_b32 s12, s4, 6
	s_add_i32 s12, s12, s8
	v_or_b32_e32 v112, s12, v227
	v_mul_lo_u32 v112, v112, s46
	v_mov_b32_e32 v113, 0
	v_lshl_add_u64 v[112:113], v[112:113], 1, v[216:217]
	flat_load_dwordx4 v[116:119], v[112:113] offset:32
	flat_load_dwordx4 v[120:123], v[112:113] offset:64
	flat_load_dwordx4 v[124:127], v[112:113] offset:96
	flat_load_dwordx4 v[112:115], v[112:113]
.Lwq_nopf:
	v_subrev_u32_e32 v233, 64, v233
	v_fma_f32 v4, -v2, v3, 1.0
	v_fmac_f32_e32 v3, v4, v3
	v_div_scale_f32 v4, vcc, 1.0, v0, 1.0
	v_mul_f32_e32 v5, v4, v3
	v_fma_f32 v6, -v2, v5, v4
	v_fmac_f32_e32 v5, v6, v3
	v_fma_f32 v2, -v2, v5, v4
	v_div_fmas_f32 v2, v2, v3, v5
	v_div_fixup_f32 v6, v2, v0, 1.0
	v_pk_mul_f32 v[32:33], v[32:33], v[6:7] op_sel_hi:[1,0]
	v_pk_mul_f32 v[2:3], v[34:35], v[6:7] op_sel_hi:[1,0]
	v_pk_mul_f32 v[34:35], v[36:37], v[6:7] op_sel_hi:[1,0]
	v_pk_mul_f32 v[4:5], v[38:39], v[6:7] op_sel_hi:[1,0]
	v_lshlrev_b32_e32 v0, 11, v234
	v_cvt_pk_bf16_f32 v5, v4, v5
	v_cvt_pk_bf16_f32 v4, v34, v35
	v_cvt_pk_bf16_f32 v3, v2, v3
	v_cvt_pk_bf16_f32 v2, v32, v33
	v_lshl_add_u64 v[8:9], v[218:219], 0, v[0:1]
	v_pk_mul_f32 v[10:11], v[48:49], v[6:7] op_sel_hi:[1,0]
	v_pk_mul_f32 v[12:13], v[50:51], v[6:7] op_sel_hi:[1,0]
	v_pk_mul_f32 v[14:15], v[52:53], v[6:7] op_sel_hi:[1,0]
	v_pk_mul_f32 v[48:49], v[54:55], v[6:7] op_sel_hi:[1,0]
	v_permlane32_swap_b32_e32 v2, v4
	v_permlane32_swap_b32_e32 v3, v5
	flat_store_dwordx4 v[8:9], v[2:5]
	v_pk_mul_f32 v[34:35], v[40:41], v[6:7] op_sel_hi:[1,0]
	v_pk_mul_f32 v[36:37], v[44:45], v[6:7] op_sel_hi:[1,0]
	v_cvt_pk_bf16_f32 v5, v48, v49
	v_cvt_pk_bf16_f32 v4, v14, v15
	v_cvt_pk_bf16_f32 v3, v12, v13
	v_cvt_pk_bf16_f32 v2, v10, v11
	s_nop 1
	v_permlane32_swap_b32_e32 v2, v4
	v_permlane32_swap_b32_e32 v3, v5
	flat_store_dwordx4 v[8:9], v[2:5] offset:64
	v_pk_mul_f32 v[10:11], v[56:57], v[6:7] op_sel_hi:[1,0]
	v_pk_mul_f32 v[12:13], v[58:59], v[6:7] op_sel_hi:[1,0]
	v_pk_mul_f32 v[2:3], v[42:43], v[6:7] op_sel_hi:[1,0]
	v_pk_mul_f32 v[4:5], v[46:47], v[6:7] op_sel_hi:[1,0]
	v_cvt_pk_bf16_f32 v3, v2, v3
	v_cvt_pk_bf16_f32 v5, v4, v5
	v_cvt_pk_bf16_f32 v4, v36, v37
	v_cvt_pk_bf16_f32 v2, v34, v35
	v_pk_mul_f32 v[14:15], v[60:61], v[6:7] op_sel_hi:[1,0]
	v_pk_mul_f32 v[32:33], v[62:63], v[6:7] op_sel_hi:[1,0]
	v_permlane32_swap_b32_e32 v2, v4
	v_permlane32_swap_b32_e32 v3, v5
	flat_store_dwordx4 v[8:9], v[2:5] offset:32
	s_nop 1
	v_cvt_pk_bf16_f32 v5, v32, v33
	v_cvt_pk_bf16_f32 v4, v14, v15
	v_cvt_pk_bf16_f32 v3, v12, v13
	v_cvt_pk_bf16_f32 v2, v10, v11
	s_nop 1
	v_permlane32_swap_b32_e32 v2, v4
	v_permlane32_swap_b32_e32 v3, v5
	flat_store_dwordx4 v[8:9], v[2:5] offset:96
	s_cmp_eq_u32 s4, 4
	s_cbranch_scc1 .LBB0_930
.LBB0_923:
	s_lshl_b32 s12, s4, 6
	s_add_i32 s12, s12, s8
	s_max_u32 s0, s4, 2
	s_and_b64 s[2:3], s[18:19], exec
	s_cselect_b32 s9, s0, s4
	s_or_b32 s0, s4, 4
	s_min_u32 s10, s0, s15
	v_or_b32_e32 v234, s12, v227
	v_mov_b32_e32 v47, 0
	s_cmp_gt_u32 s9, s10
	v_mov_b32_e32 v46, 0
	v_mov_b32_e32 v45, 0
	v_mov_b32_e32 v44, 0
	v_mov_b32_e32 v43, 0
	v_mov_b32_e32 v42, 0
	v_mov_b32_e32 v41, 0
	v_mov_b32_e32 v40, 0
	v_mov_b32_e32 v39, 0
	v_mov_b32_e32 v38, 0
	v_mov_b32_e32 v37, 0
	v_mov_b32_e32 v36, 0
	v_mov_b32_e32 v35, 0
	v_mov_b32_e32 v34, 0
	v_mov_b32_e32 v33, 0
	v_mov_b32_e32 v32, 0
	v_mov_b32_e32 v63, 0
	v_mov_b32_e32 v62, 0
	v_mov_b32_e32 v61, 0
	v_mov_b32_e32 v60, 0
	v_mov_b32_e32 v59, 0
	v_mov_b32_e32 v58, 0
	v_mov_b32_e32 v57, 0
	v_mov_b32_e32 v56, 0
	v_mov_b32_e32 v55, 0
	v_mov_b32_e32 v54, 0
	v_mov_b32_e32 v53, 0
	v_mov_b32_e32 v52, 0
	v_mov_b32_e32 v51, 0
	v_mov_b32_e32 v50, 0
	v_mov_b32_e32 v49, 0
	v_mov_b32_e32 v48, 0
	v_mov_b32_e32 v235, v229
	s_cbranch_scc1 .LBB0_922
	s_cmp_lg_u32 s4, 0
	s_cbranch_scc1 .Lwq_have
	v_mul_lo_u32 v0, v234, s46
	v_lshl_add_u64 v[2:3], v[0:1], 1, v[216:217]
	flat_load_dwordx4 v[112:115], v[2:3]
	flat_load_dwordx4 v[116:119], v[2:3] offset:32
	flat_load_dwordx4 v[120:123], v[2:3] offset:64
	flat_load_dwordx4 v[124:127], v[2:3] offset:96
	s_waitcnt vmcnt(0)
.Lwq_have:
	v_sub_u32_e32 v0, 0x87f, v234
	v_subrev_u32_e32 v2, s24, v234
	s_lshl_b32 s0, s9, 10
	v_lshl_add_u32 v2, v2, 2, 0
	v_min_i32_e32 v236, 0x100, v0
	v_add_u32_e32 v0, s0, v230
	v_add_u32_e32 v2, 0x20400, v2
	ds_read_b128 v[140:143], v0 offset:49664
	ds_read_b128 v[128:131], v0
	ds_read_b128 v[132:135], v0 offset:512
	ds_read_b128 v[136:139], v0 offset:16384
	ds_read_b128 v[144:147], v0 offset:16896
	ds_read_b32 v237, v2
	ds_read_b128 v[148:151], v0 offset:32768
	ds_read_b128 v[152:155], v0 offset:33280
	ds_read_b128 v[156:159], v0 offset:49152
	v_mov_b32_e32 v14, v1
	v_mov_b32_e32 v15, v1
	v_mov_b32_e32 v0, v1
	v_mov_b32_e32 v2, v1
	v_mov_b32_e32 v3, v1
	v_mov_b32_e32 v4, v1
	v_mov_b32_e32 v5, v1
	v_mov_b32_e32 v6, v1
	v_mov_b32_e32 v7, v1
	v_mov_b32_e32 v8, v1
	v_mov_b32_e32 v9, v1
	v_mov_b32_e32 v10, v1
	v_mov_b32_e32 v11, v1
	v_mov_b32_e32 v12, v1
	v_mov_b32_e32 v13, v1
	v_mov_b64_e32 v[46:47], v[14:15]
	v_mov_b64_e32 v[62:63], v[14:15]
	v_mov_b64_e32 v[78:79], v[30:31]
	s_add_i32 s11, s12, 0xffffff9f
	s_addk_i32 s12, 0x41
	v_lshl_or_b32 v238, s9, 12, v215
	v_lshl_or_b32 v239, s9, 8, v214
	v_add_u32_e32 v240, s0, v232
	s_lshl_b32 s13, s9, 6
	s_mov_b32 s14, s24
	v_mov_b32_e32 v241, v233
	v_mov_b32_e32 v242, v228
	v_mov_b32_e32 v235, v229
	v_mov_b64_e32 v[44:45], v[12:13]
	v_mov_b64_e32 v[42:43], v[10:11]
	v_mov_b64_e32 v[40:41], v[8:9]
	v_mov_b64_e32 v[38:39], v[6:7]
	v_mov_b64_e32 v[36:37], v[4:5]
	v_mov_b64_e32 v[34:35], v[2:3]
	v_mov_b64_e32 v[32:33], v[0:1]
	v_mov_b64_e32 v[60:61], v[12:13]
	v_mov_b64_e32 v[58:59], v[10:11]
	v_mov_b64_e32 v[56:57], v[8:9]
	v_mov_b64_e32 v[54:55], v[6:7]
	v_mov_b64_e32 v[52:53], v[4:5]
	v_mov_b64_e32 v[50:51], v[2:3]
	v_mov_b64_e32 v[48:49], v[0:1]
	v_mov_b64_e32 v[76:77], v[28:29]
	v_mov_b64_e32 v[74:75], v[26:27]
	v_mov_b64_e32 v[72:73], v[24:25]
	v_mov_b64_e32 v[70:71], v[22:23]
	v_mov_b64_e32 v[68:69], v[20:21]
	v_mov_b64_e32 v[66:67], v[18:19]
	v_mov_b64_e32 v[64:65], v[16:17]
	s_branch .LBB0_926

.LBB0_926:
	v_add_u32_e32 v0, 0, v238
	v_add_u32_e32 v2, 0x10000, v0
	v_add_u32_e32 v3, 0x10200, v0
	v_add_u32_e32 v4, 0x10400, v0
	v_add_u32_e32 v5, 0x10600, v0
	ds_read_b64_tr_b16 v[188:189], v2
	ds_read_b64_tr_b16 v[190:191], v3
	ds_read_b64_tr_b16 v[176:177], v4
	ds_read_b64_tr_b16 v[178:179], v5
	v_add_u32_e32 v2, 0x10800, v0
	v_add_u32_e32 v3, 0x10a00, v0
	v_add_u32_e32 v4, 0x10c00, v0
	v_add_u32_e32 v5, 0x10e00, v0
	ds_read_b64_tr_b16 v[172:173], v2
	ds_read_b64_tr_b16 v[174:175], v3
	ds_read_b64_tr_b16 v[164:165], v4
	ds_read_b64_tr_b16 v[166:167], v5
	s_waitcnt vmcnt(4) lgkmcnt(0)
	v_mfma_f32_32x32x16_bf16 v[80:95], v[132:135], v[112:115], v[64:79]
	v_add_u32_e32 v2, 0x18000, v0
	ds_read_b64_tr_b16 v[184:185], v2
	v_add_u32_e32 v2, 0x18200, v0
	ds_read_b64_tr_b16 v[186:187], v2
	v_add_u32_e32 v2, 0x18400, v0
	ds_read_b64_tr_b16 v[180:181], v2
	v_add_u32_e32 v2, 0x18600, v0
	v_mfma_f32_32x32x16_bf16 v[96:111], v[128:131], v[112:115], v[64:79]
	ds_read_b64_tr_b16 v[182:183], v2
	v_add_u32_e32 v2, 0x18800, v0
	ds_read_b64_tr_b16 v[168:169], v2
	v_add_u32_e32 v2, 0x18a00, v0
	ds_read_b64_tr_b16 v[170:171], v2
	v_add_u32_e32 v2, 0x18c00, v0
	v_add_u32_e32 v0, 0x18e00, v0
	v_mfma_f32_32x32x16_bf16 v[80:95], v[144:147], v[116:119], v[80:95]
	ds_read_b64_tr_b16 v[160:161], v2
	ds_read_b64_tr_b16 v[162:163], v0
	s_cmp_ge_u32 s9, s10
	s_cselect_b64 s[2:3], -1, 0
	s_and_b64 vcc, exec, s[2:3]
	v_mfma_f32_32x32x16_bf16 v[96:111], v[136:139], v[116:119], v[96:111]
	v_mfma_f32_32x32x16_bf16 v[80:95], v[152:155], v[120:123], v[80:95]
	v_mfma_f32_32x32x16_bf16 v[96:111], v[148:151], v[120:123], v[96:111]
	v_mfma_f32_32x32x16_bf16 v[80:95], v[140:143], v[124:127], v[80:95]
	v_mfma_f32_32x32x16_bf16 v[96:111], v[156:159], v[124:127], v[96:111]
	s_cbranch_vccnz .LBB0_928
	v_add_u32_e32 v0, 0, v240
	ds_read_b128 v[128:131], v0
	ds_read_b128 v[132:135], v0 offset:512
	ds_read_b128 v[136:139], v0 offset:16384
	ds_read_b128 v[144:147], v0 offset:16896
	ds_read_b128 v[148:151], v0 offset:32768
	ds_read_b128 v[152:155], v0 offset:33280
	ds_read_b128 v[156:159], v0 offset:49152
	ds_read_b128 v[140:143], v0 offset:49664
